# v048_nt2
# baseline (speedup 1.0000x reference)
.LBB0_558:
	v_lshl_or_b32 v206, s12, 8, v248
	s_lshl_b32 s13, s13, 8
	v_add_u32_e32 v128, s13, v246
	v_ashrrev_i32_e32 v207, 31, v206
	v_lshlrev_b64 v[222:223], 1, v[206:207]
	v_ashrrev_i32_e32 v129, 31, v128
	v_lshl_add_u64 v[126:127], s[66:67], 0, v[222:223]
	v_lshlrev_b64 v[224:225], 12, v[128:129]
	v_lshl_add_u64 v[122:123], v[126:127], 0, v[224:225]
	global_load_dwordx4 v[190:193], v[122:123], off nt
	global_load_dwordx4 v[186:189], v[122:123], off offset:256 nt
	v_or_b32_e32 v220, 16, v128
	v_ashrrev_i32_e32 v221, 31, v220
	v_lshlrev_b64 v[122:123], 12, v[220:221]
	v_or_b32_e32 v218, 32, v128
	v_lshl_add_u64 v[122:123], v[126:127], 0, v[122:123]
	v_ashrrev_i32_e32 v219, 31, v218
	global_load_dwordx4 v[182:185], v[122:123], off nt
	global_load_dwordx4 v[178:181], v[122:123], off offset:256 nt
	v_lshlrev_b64 v[122:123], 12, v[218:219]
	v_or_b32_e32 v216, 48, v128
	v_lshl_add_u64 v[122:123], v[126:127], 0, v[122:123]
	v_ashrrev_i32_e32 v217, 31, v216
	global_load_dwordx4 v[174:177], v[122:123], off nt
	global_load_dwordx4 v[170:173], v[122:123], off offset:256 nt
	v_lshlrev_b64 v[122:123], 12, v[216:217]
	v_add_u32_e32 v214, 0x80, v128
	v_lshl_add_u64 v[122:123], v[126:127], 0, v[122:123]
	v_ashrrev_i32_e32 v215, 31, v214
	global_load_dwordx4 v[166:169], v[122:123], off nt
	global_load_dwordx4 v[162:165], v[122:123], off offset:256 nt
	v_lshlrev_b64 v[122:123], 12, v[214:215]
	v_add_u32_e32 v212, 0x90, v128
	v_lshl_add_u64 v[122:123], v[126:127], 0, v[122:123]
	v_ashrrev_i32_e32 v213, 31, v212
	global_load_dwordx4 v[158:161], v[122:123], off nt
	global_load_dwordx4 v[154:157], v[122:123], off offset:256 nt
	v_lshlrev_b64 v[122:123], 12, v[212:213]
	v_add_u32_e32 v210, 0xa0, v128
	v_add_u32_e32 v208, 0xb0, v128
	v_lshl_add_u64 v[122:123], v[126:127], 0, v[122:123]
	v_ashrrev_i32_e32 v211, 31, v210
	v_ashrrev_i32_e32 v209, 31, v208
	global_load_dwordx4 v[142:145], v[122:123], off nt
	global_load_dwordx4 v[138:141], v[122:123], off offset:256 nt
	v_lshlrev_b64 v[122:123], 12, v[210:211]
	v_lshlrev_b64 v[128:129], 12, v[208:209]
	v_lshl_add_u64 v[122:123], v[126:127], 0, v[122:123]
	v_lshl_add_u64 v[126:127], v[126:127], 0, v[128:129]
	global_load_dwordx4 v[130:133], v[122:123], off nt
	s_nop 0
	global_load_dwordx4 v[122:125], v[122:123], off offset:256 nt
	s_nop 0
	global_load_dwordx4 v[134:137], v[126:127], off nt
	s_nop 0
	global_load_dwordx4 v[126:129], v[126:127], off offset:256 nt
	v_and_b32_e32 v231, 64, v229
	v_xor_b32_e32 v228, 16, v229
	v_add_u32_e32 v231, 64, v231
	v_cmp_lt_i32_e32 vcc, v228, v231
	s_waitcnt vmcnt(0)
	v_lshlrev_b32_e32 v232, 16, v190
	v_and_b32_e32 v233, 0xffff0000, v190
	v_lshlrev_b32_e32 v190, 16, v191
	v_and_b32_e32 v191, 0xffff0000, v191
	v_pk_add_f32 v[152:153], v[152:153], v[190:191]
	v_pk_add_f32 v[150:151], v[150:151], v[232:233]
	v_lshlrev_b32_e32 v190, 16, v192
	v_and_b32_e32 v191, 0xffff0000, v192
	v_lshlrev_b32_e32 v192, 16, v193
	v_and_b32_e32 v193, 0xffff0000, v193
	v_pk_add_f32 v[192:193], v[148:149], v[192:193]
	v_pk_add_f32 v[148:149], v[146:147], v[190:191]
	v_mul_f32_e32 v146, v151, v151
	v_mul_f32_e32 v147, v153, v153
	v_fmac_f32_e32 v146, v150, v150
	v_fmac_f32_e32 v147, v152, v152
	v_add_f32_e32 v146, v146, v147
	v_mul_f32_e32 v147, v149, v149
	v_mul_f32_e32 v190, v193, v193
	v_fmac_f32_e32 v147, v148, v148
	v_fmac_f32_e32 v190, v192, v192
	v_add_f32_e32 v147, v147, v190
	v_add_f32_e32 v190, v146, v147
	v_cvt_pk_bf16_f32 v146, v150, v151
	v_lshl_add_u64 v[150:151], s[66:67], 0, v[224:225]
	v_cvt_pk_bf16_f32 v147, v152, v153
	v_cvt_pk_bf16_f32 v148, v148, v149
	v_cvt_pk_bf16_f32 v149, v192, v193
	v_lshl_add_u64 v[150:151], v[150:151], 0, v[222:223]
	global_store_dwordx4 v[150:151], v[146:149], off
	v_cndmask_b32_e32 v228, v229, v228, vcc
	v_lshlrev_b32_e32 v228, 2, v228
	v_lshlrev_b32_e32 v146, 16, v186
	v_and_b32_e32 v147, 0xffff0000, v186
	v_lshlrev_b32_e32 v148, 16, v187
	v_and_b32_e32 v149, 0xffff0000, v187
	v_pk_add_f32 v[120:121], v[120:121], v[148:149]
	v_pk_add_f32 v[118:119], v[118:119], v[146:147]
	v_lshlrev_b32_e32 v146, 16, v188
	v_and_b32_e32 v147, 0xffff0000, v188
	v_lshlrev_b32_e32 v148, 16, v189
	v_and_b32_e32 v149, 0xffff0000, v189
	v_pk_add_f32 v[148:149], v[116:117], v[148:149]
	v_pk_add_f32 v[116:117], v[114:115], v[146:147]
	v_mul_f32_e32 v114, v119, v119
	v_mul_f32_e32 v115, v121, v121
	v_fmac_f32_e32 v114, v118, v118
	v_fmac_f32_e32 v115, v120, v120
	v_add_f32_e32 v114, v114, v115
	v_mul_f32_e32 v115, v117, v117
	v_mul_f32_e32 v146, v149, v149
	v_fmac_f32_e32 v115, v116, v116
	v_fmac_f32_e32 v146, v148, v148
	v_add_f32_e32 v115, v115, v146
	v_add_f32_e32 v114, v114, v115
	v_add_f32_e32 v146, v190, v114
	v_cvt_pk_bf16_f32 v114, v118, v119
	v_cvt_pk_bf16_f32 v115, v120, v121
	v_cvt_pk_bf16_f32 v116, v116, v117
	v_cvt_pk_bf16_f32 v117, v148, v149
	global_store_dwordx4 v[150:151], v[114:117], off offset:256
	s_nop 1
	v_mov_b32_e32 v114, v146
	s_nop 1
	v_permlane32_swap_b32_e32 v146, v114
	v_add_f32_e32 v114, v146, v114
	ds_bpermute_b32 v115, v228, v114
	s_and_saveexec_b64 s[22:23], s[38:39]
	s_cbranch_execz .LBB0_560
	s_waitcnt lgkmcnt(0)
	v_add_f32_e32 v114, v114, v115
	ds_write_b32 v250, v114
